# even-layer mixer->G2 barrier XCD-local too (conv tiles mapped to the XCD's GEMM token rows), on stack15
# baseline (speedup 1.0000x reference)
; #define LAS __attribute__((address_space(3)))
; __device__ __forceinline__ void mixb_item(const Args& A, int li, int item, LAS unsigned char* lds, int tid, int lane, int wave) {
;     const int row0 = item * 32, bb = row0 >> 13, pos0 = row0 & 8191;
;     const bf16_t* Gb = (const bf16_t*)(A.ws + WS_GB); bf16_t* CAT = (bf16_t*)(A.ws + WS_CAT);
;     const float* cw = A.in[10] + (size_t)li * 31 * 512; const float* cb = A.in[11] + li * 512; const float* ng = A.in[12] + li * 512; const float* nb = A.in[13] + li * 512;
;     LAS float* cv = (LAS float*)(lds + 65536);
;     {
;         u32x4 st[8];
; #pragma unroll
;         for (int i = 0; i < 8; ++i) { const int idx = tid + NTHR * i, row = idx >> 6, ch = idx & 63, pos = pos0 - 15 + row; const bool ok = idx < 62 * 64 && pos >= 0 && pos < SEQ;
;             st[i] = ok ? *(const u32x4*)(Gb + ((size_t)bb * SEQ + (ok ? pos : pos0)) * 512 + ch * 8) : (u32x4){0u, 0u, 0u, 0u}; }
.LBB0_440:
	s_cmpk_lt_i32 s2, 0x100
	s_cbranch_scc1 .LBB0_437
	s_and_b32 s14, s2, 7
	s_lshl_b32 s14, s14, 6
	s_bfe_u32 s100, s2, 0x50003
	s_or_b32 s14, s14, s100
	s_lshr_b32 s100, s2, 8
	s_add_i32 s100, s100, -1
	s_lshl_b32 s100, s100, 5
	s_or_b32 s14, s14, s100
	s_add_i32 s14, s14, 0x100
	s_lshl_b32 s14, s14, 5
	s_and_b32 s20, s14, 0x1fe0
	s_add_i32 s20, s20, -15
	v_add_u32_e32 v1, s20, v156
	s_movk_i32 s21, 0x2000
	s_add_i32 s11, s14, 0xffffe000
	v_cmp_gt_u32_e32 vcc, s21, v1
	s_and_b32 s14, s11, 0x2000
	s_and_b64 s[22:23], s[0:1], vcc
	v_mov_b32_e32 v0, 0
	v_mov_b32_e32 v4, 0
	v_mov_b32_e32 v5, 0
	v_mov_b32_e32 v6, 0
	v_mov_b32_e32 v7, 0
	s_and_saveexec_b64 s[34:35], s[22:23]
	s_cbranch_execz .LBB0_443
	v_or_b32_e32 v1, s14, v1
	v_lshlrev_b32_e32 v2, 10, v1
	v_mov_b32_e32 v3, v177
	v_lshl_add_u64 v[2:3], v[120:121], 0, v[2:3]
	global_load_dwordx4 v[4:7], v[2:3], off

; __device__ __forceinline__ unsigned xb_add(unsigned* p, unsigned v) { return __hip_atomic_fetch_add(p, v, __ATOMIC_RELAXED, __HIP_MEMORY_SCOPE_AGENT); }
; __device__ __forceinline__ void xcd_barrier(const XcdBarrier& b) {
;     ...
;     if (threadIdx.x == 0) {
;         unsigned* bar = b.bar;
;         __builtin_amdgcn_s_waitcnt(0);
;         unsigned nloc = b.st[0], nx = b.st[1];
;         if (nloc == 0u) { xcd_barrier_complete(bar, b.x, nloc, nx); b.st[0] = nloc; b.st[1] = nx; }
;         const unsigned old = xb_add(&bar[XB_XSUB(b.x)], 1u);
;         const unsigned gen = old / nloc;
;         if (old + 1u == (gen + 1u) * nloc) {
;             __builtin_amdgcn_fence(__ATOMIC_RELEASE, "agent");
;             asm volatile("s_waitcnt vmcnt(0)" ::: "memory");
;             const unsigned og = xb_add(&bar[XB_TOP], 1u);
;             const unsigned tg = og / nx;
;             if (og + 1u == (tg + 1u) * nx) xb_add(&bar[XB_TOPGEN], 1u);
.LBB0_509:
	v_readlane_b32 s4, v253, 35
	v_readlane_b32 s5, v253, 36
	v_cvt_f32_u32_e32 v1, v2
	v_sub_u32_e32 v4, 0, v2
	v_rcp_iflag_f32_e32 v1, v1
	s_nop 1
	global_atomic_add v3, v177, v238, s[4:5] sc0
	v_mul_f32_e32 v1, 0x4f7ffffe, v1
	v_cvt_u32_f32_e32 v1, v1
	v_mul_lo_u32 v4, v4, v1
	v_mul_hi_u32 v4, v1, v4
	v_add_u32_e32 v1, v1, v4
	s_waitcnt vmcnt(0)
	v_mul_hi_u32 v1, v3, v1
	v_mul_lo_u32 v4, v1, v2
	v_sub_u32_e32 v4, v3, v4
	v_add_u32_e32 v5, 1, v1
	v_cmp_ge_u32_e32 vcc, v4, v2
	v_add_u32_e32 v3, 1, v3
	s_nop 0
	v_cndmask_b32_e32 v1, v1, v5, vcc
	v_sub_u32_e32 v5, v4, v2
	v_cndmask_b32_e32 v4, v4, v5, vcc
	v_add_u32_e32 v5, 1, v1
	v_cmp_ge_u32_e32 vcc, v4, v2
	s_nop 1
	v_cndmask_b32_e32 v1, v1, v5, vcc
	v_mul_lo_u32 v4, v2, v1
	v_add_u32_e32 v2, v4, v2
	v_cmp_ne_u32_e32 vcc, v3, v2
	s_waitcnt lgkmcnt(0)
	v_add_u32_e32 v4, 1, v1
	v_mul_lo_u32 v4, v4, v0
	v_mov_b32_e32 v6, 0x21ff8
	ds_read_b32 v6, v6
	v_readlane_b32 s98, v253, 39
	v_readlane_b32 s99, v253, 40
	s_nop 4
	s_waitcnt lgkmcnt(0)
	v_readfirstlane_b32 s100, v6
	s_cmp_eq_u32 s100, 0
	s_cbranch_scc0 .Lxb_b2_full
	v_readlane_b32 s100, v254, 53
	s_bitcmp0_b32 s100, 0
	s_cbranch_scc0 .Lxb_b2_full
	s_cbranch_vccnz .Lxb_b2_lnl
	buffer_inv sc1
	s_waitcnt vmcnt(0)
	global_atomic_add v177, v238, s[98:99]
	s_branch .Lxb_b2_done
